# P2 light pass: row stores issued in the next trip after its loads (wait no longer covers them) + next-row cache warm-up loads
# speedup vs baseline: 1.0153x; 1.0042x over previous
.LBB0_370:
	s_cmp_lt_i32 s36, 3
	s_cselect_b64 s[0:1], -1, 0
	s_cmp_gt_i32 s37, 2
	s_cselect_b64 s[2:3], -1, 0
	s_and_b64 s[0:1], s[0:1], s[2:3]
	s_andn2_b64 vcc, exec, s[0:1]
	s_cbranch_vccnz .LBB0_493
	v_readlane_b32 s4, v254, 2
	v_readlane_b32 s5, v254, 3
	v_mbcnt_lo_u32_b32 v134, -1, 0
	v_mbcnt_hi_u32_b32 v134, -1, v134
	v_lshlrev_b32_e32 v105, 4, v134
	s_load_dwordx2 s[0:1], s[4:5], 0x100
	v_readlane_b32 s2, v254, 0
	s_cmp_gt_i32 s2, 63
	v_readlane_b32 s3, v254, 1
	s_cselect_b32 s6, 32, 0
	s_cmp_ge_i32 s87, s6
	s_mov_b64 s[2:3], -1
	s_cbranch_scc0 .LBB0_406
	s_sub_i32 s2, s87, s6
	s_lshl_b32 s2, s2, 3
	s_add_i32 s2, s2, s94
	s_cmpk_gt_i32 s2, 0x7fff
	s_cbranch_scc1 .LBB0_405
	s_load_dwordx2 s[8:9], s[4:5], 0x38
	s_load_dwordx2 s[12:13], s[4:5], 0x48
	v_lshlrev_b32_e32 v6, 1, v134
	s_waitcnt vmcnt(0)
	v_lshlrev_b32_e32 v4, 2, v134
	v_ashrrev_i32_e32 v7, 31, v6
	v_ashrrev_i32_e32 v5, 31, v4
	s_waitcnt lgkmcnt(0)
	v_lshl_add_u64 v[0:1], v[6:7], 2, s[12:13]
	global_load_dwordx2 v[68:69], v[0:1], off
	v_lshl_add_u64 v[0:1], v[4:5], 2, s[8:9]
	global_load_dwordx4 v[0:3], v[0:1], off
	v_ashrrev_i32_e32 v8, 4, v134
	v_lshlrev_b32_e64 v84, v8, 2
	v_lshlrev_b32_e32 v8, 3, v134
	v_ashrrev_i32_e32 v9, 31, v8
	v_lshlrev_b64 v[8:9], 1, v[8:9]
	v_lshl_add_u64 v[10:11], s[0:1], 0, v[8:9]
	s_mov_b64 s[8:9], 0xd000000
	v_lshl_add_u64 v[70:71], v[10:11], 0, s[8:9]
	v_mbcnt_lo_u32_b32 v10, -1, 0
	v_mbcnt_hi_u32_b32 v10, -1, v10
	v_and_b32_e32 v11, 64, v10
	v_add_u32_e32 v11, 64, v11
	v_xor_b32_e32 v12, 1, v10
	v_cmp_lt_i32_e32 vcc, v12, v11
	v_readlane_b32 s4, v254, 0
	s_sub_i32 s3, s4, s6
	v_cndmask_b32_e32 v12, v10, v12, vcc
	v_lshlrev_b32_e32 v85, 2, v12
	v_xor_b32_e32 v12, 2, v10
	v_cmp_lt_i32_e32 vcc, v12, v11
	v_readlane_b32 s5, v254, 1
	s_lshl_b32 s4, s3, 3
	v_cndmask_b32_e32 v12, v10, v12, vcc
	v_lshlrev_b32_e32 v86, 2, v12
	v_xor_b32_e32 v12, 4, v10
	v_cmp_lt_i32_e32 vcc, v12, v11
	s_lshl_b32 s3, s87, 3
	s_add_i32 s3, s94, s3
	v_cndmask_b32_e32 v12, v10, v12, vcc
	v_lshlrev_b32_e32 v87, 2, v12
	v_xor_b32_e32 v12, 8, v10
	v_cmp_lt_i32_e32 vcc, v12, v11
	s_lshl_b32 s5, s6, 3
	s_sub_i32 s3, s3, s5
	v_cndmask_b32_e32 v12, v10, v12, vcc
	v_lshlrev_b32_e32 v88, 2, v12
	v_xor_b32_e32 v12, 16, v10
	v_cmp_lt_i32_e32 vcc, v12, v11
	s_add_i32 s6, s3, -15
	s_ashr_i32 s3, s2, 31
	v_cndmask_b32_e32 v12, v10, v12, vcc
	v_lshlrev_b32_e32 v89, 2, v12
	v_xor_b32_e32 v12, 32, v10
	v_cmp_lt_i32_e32 vcc, v12, v11
	s_lshl_b64 s[8:9], s[2:3], 8
	s_ashr_i32 s5, s4, 31
	v_cndmask_b32_e32 v10, v10, v12, vcc
	s_lshl_b64 s[12:13], s[2:3], 9
	s_lshl_b64 s[2:3], s[2:3], 10
	v_lshlrev_b32_e32 v90, 2, v10
	v_lshl_add_u64 v[72:73], v[6:7], 1, s[8:9]
	s_lshl_b64 s[8:9], s[4:5], 8
	v_lshl_add_u64 v[74:75], v[4:5], 1, s[12:13]
	s_lshl_b64 s[12:13], s[4:5], 9
	v_lshl_add_u64 v[76:77], s[2:3], 0, v[8:9]
	s_lshl_b64 s[14:15], s[4:5], 10
	s_mov_b32 s5, 0x10a00000
	s_mov_b32 s16, 0xf000000
	v_mov_b32_e32 v91, 0x358637bd
	s_mov_b32 s17, 0x800000
	s_mov_b32 s18, 0x12a00000
	s_brev_b32 s19, 8
	s_mov_b32 s24, 0
	s_branch .LBB0_375
.LBB0_374:
	s_or_b64 exec, exec, s[2:3]
	s_cmp_eq_u32 s24, 0
	s_cbranch_scc1 .Lp2_first
	global_store_dwordx4 v[150:151], v[152:155], off
	global_store_dwordx2 v[156:157], v[158:159], off
	global_store_dword v[160:161], v162, off
	s_add_i32 s22, s6, s4
	s_ashr_i32 s23, s22, 31
	s_lshl_b64 s[22:23], s[22:23], 10
	s_add_u32 s22, s22, s0
	s_addc_u32 s23, s23, s1
	s_add_u32 s22, s22, 0xd000000
	s_addc_u32 s23, s23, 0
	global_load_dwordx4 v[136:139], v105, s[22:23]
	global_load_dwordx4 v[136:139], v105, s[22:23] offset:1024
	global_load_dwordx4 v[136:139], v105, s[22:23] offset:2048
	global_load_dwordx4 v[136:139], v105, s[22:23] offset:3072
	s_add_u32 s22, s22, 0x1000
	s_addc_u32 s23, s23, 0
	global_load_dwordx4 v[136:139], v105, s[22:23]
	global_load_dwordx4 v[136:139], v105, s[22:23] offset:1024
	global_load_dwordx4 v[136:139], v105, s[22:23] offset:2048
	global_load_dwordx4 v[136:139], v105, s[22:23] offset:3072
	s_add_u32 s22, s22, 0x1000
	s_addc_u32 s23, s23, 0
	global_load_dwordx4 v[136:139], v105, s[22:23]
	global_load_dwordx4 v[136:139], v105, s[22:23] offset:1024
	global_load_dwordx4 v[136:139], v105, s[22:23] offset:2048
	global_load_dwordx4 v[136:139], v105, s[22:23] offset:3072
	s_add_u32 s22, s22, 0x1000
	s_addc_u32 s23, s23, 0
	global_load_dwordx4 v[136:139], v105, s[22:23]
	global_load_dwordx4 v[136:139], v105, s[22:23] offset:1024
	global_load_dwordx4 v[136:139], v105, s[22:23] offset:2048
	global_load_dwordx4 v[136:139], v105, s[22:23] offset:3072
	v_lshl_add_u64 v[140:141], v[100:101], 0, s[8:9]
	global_load_dword v136, v[140:141], off
	s_add_u32 s22, s12, s16
	s_addc_u32 s23, s13, 0
	v_lshl_add_u64 v[142:143], s[0:1], 0, v[74:75]
	v_lshl_add_u64 v[142:143], v[142:143], 0, s[22:23]
	global_load_dwordx2 v[136:137], v[142:143], off
	s_waitcnt vmcnt(21)
	s_branch .Lp2_go
.Lp2_first:
	s_add_i32 s22, s6, s4
	s_ashr_i32 s23, s22, 31
	s_lshl_b64 s[22:23], s[22:23], 10
	s_add_u32 s22, s22, s0
	s_addc_u32 s23, s23, s1
	s_add_u32 s22, s22, 0xd000000
	s_addc_u32 s23, s23, 0
	global_load_dwordx4 v[136:139], v105, s[22:23]
	global_load_dwordx4 v[136:139], v105, s[22:23] offset:1024
	global_load_dwordx4 v[136:139], v105, s[22:23] offset:2048
	global_load_dwordx4 v[136:139], v105, s[22:23] offset:3072
	s_add_u32 s22, s22, 0x1000
	s_addc_u32 s23, s23, 0
	global_load_dwordx4 v[136:139], v105, s[22:23]
	global_load_dwordx4 v[136:139], v105, s[22:23] offset:1024
	global_load_dwordx4 v[136:139], v105, s[22:23] offset:2048
	global_load_dwordx4 v[136:139], v105, s[22:23] offset:3072
	s_add_u32 s22, s22, 0x1000
	s_addc_u32 s23, s23, 0
	global_load_dwordx4 v[136:139], v105, s[22:23]
	global_load_dwordx4 v[136:139], v105, s[22:23] offset:1024
	global_load_dwordx4 v[136:139], v105, s[22:23] offset:2048
	global_load_dwordx4 v[136:139], v105, s[22:23] offset:3072
	s_add_u32 s22, s22, 0x1000
	s_addc_u32 s23, s23, 0
	global_load_dwordx4 v[136:139], v105, s[22:23]
	global_load_dwordx4 v[136:139], v105, s[22:23] offset:1024
	global_load_dwordx4 v[136:139], v105, s[22:23] offset:2048
	global_load_dwordx4 v[136:139], v105, s[22:23] offset:3072
	v_lshl_add_u64 v[140:141], v[100:101], 0, s[8:9]
	global_load_dword v136, v[140:141], off
	s_add_u32 s22, s12, s16
	s_addc_u32 s23, s13, 0
	v_lshl_add_u64 v[142:143], s[0:1], 0, v[74:75]
	v_lshl_add_u64 v[142:143], v[142:143], 0, s[22:23]
	global_load_dwordx2 v[136:137], v[142:143], off
	s_waitcnt vmcnt(18)
.Lp2_go:
	v_lshlrev_b32_e32 v94, 16, v24
	v_and_b32_e32 v95, 0xffff0000, v24
	v_lshlrev_b32_e32 v82, 16, v25
	v_and_b32_e32 v83, 0xffff0000, v25
	v_lshlrev_b32_e32 v80, 16, v26
	v_and_b32_e32 v81, 0xffff0000, v26
	v_lshlrev_b32_e32 v24, 16, v27
	v_and_b32_e32 v25, 0xffff0000, v27
	v_lshlrev_b32_e32 v26, 16, v8
	v_and_b32_e32 v27, 0xffff0000, v8
	v_lshlrev_b32_e32 v8, 16, v9
	v_and_b32_e32 v9, 0xffff0000, v9
	v_lshlrev_b32_e32 v96, 16, v4
	v_and_b32_e32 v97, 0xffff0000, v4
	v_pk_add_f32 v[8:9], v[82:83], v[8:9]
	v_lshlrev_b32_e32 v4, 16, v5
	v_and_b32_e32 v5, 0xffff0000, v5
	v_pk_add_f32 v[4:5], v[8:9], v[4:5]
	v_lshlrev_b32_e32 v8, 16, v21
	v_and_b32_e32 v9, 0xffff0000, v21
	v_pk_add_f32 v[4:5], v[4:5], v[8:9]
	v_lshlrev_b32_e32 v8, 16, v13
	v_and_b32_e32 v9, 0xffff0000, v13
	v_pk_add_f32 v[4:5], v[4:5], v[8:9]
	v_lshlrev_b32_e32 v8, 16, v37
	v_and_b32_e32 v9, 0xffff0000, v37
	v_pk_add_f32 v[26:27], v[94:95], v[26:27]
	v_pk_add_f32 v[4:5], v[4:5], v[8:9]
	v_lshlrev_b32_e32 v8, 16, v29
	v_and_b32_e32 v9, 0xffff0000, v29
	v_pk_add_f32 v[26:27], v[26:27], v[96:97]
	v_lshlrev_b32_e32 v96, 16, v20
	v_and_b32_e32 v97, 0xffff0000, v20
	v_pk_add_f32 v[8:9], v[4:5], v[8:9]
	v_lshlrev_b32_e32 v4, 16, v10
	v_and_b32_e32 v5, 0xffff0000, v10
	v_pk_add_f32 v[26:27], v[26:27], v[96:97]
	v_lshlrev_b32_e32 v96, 16, v12
	v_and_b32_e32 v97, 0xffff0000, v12
	v_pk_add_f32 v[4:5], v[80:81], v[4:5]
	v_lshlrev_b32_e32 v12, 16, v6
	v_and_b32_e32 v13, 0xffff0000, v6
	v_pk_add_f32 v[4:5], v[4:5], v[12:13]
	v_lshlrev_b32_e32 v12, 16, v22
	v_and_b32_e32 v13, 0xffff0000, v22
	v_pk_add_f32 v[4:5], v[4:5], v[12:13]
	v_lshlrev_b32_e32 v12, 16, v14
	v_and_b32_e32 v13, 0xffff0000, v14
	v_pk_add_f32 v[4:5], v[4:5], v[12:13]
	v_lshlrev_b32_e32 v12, 16, v38
	v_and_b32_e32 v13, 0xffff0000, v38
	v_pk_add_f32 v[4:5], v[4:5], v[12:13]
	v_lshlrev_b32_e32 v12, 16, v30
	v_and_b32_e32 v13, 0xffff0000, v30
	v_pk_add_f32 v[12:13], v[4:5], v[12:13]
	v_lshlrev_b32_e32 v4, 16, v11
	v_and_b32_e32 v5, 0xffff0000, v11
	v_pk_add_f32 v[4:5], v[24:25], v[4:5]
	v_lshlrev_b32_e32 v6, 16, v7
	v_and_b32_e32 v7, 0xffff0000, v7
	v_pk_add_f32 v[4:5], v[4:5], v[6:7]
	v_lshlrev_b32_e32 v6, 16, v23
	v_and_b32_e32 v7, 0xffff0000, v23
	v_pk_add_f32 v[4:5], v[4:5], v[6:7]
	v_lshlrev_b32_e32 v6, 16, v15
	v_and_b32_e32 v7, 0xffff0000, v15
	v_lshlrev_b32_e32 v14, 16, v50
	v_and_b32_e32 v15, 0xffff0000, v50
	v_cvt_f32_i32_e32 v50, v92
	v_lshlrev_b32_e32 v20, 16, v51
	v_and_b32_e32 v21, 0xffff0000, v51
	v_pk_add_f32 v[26:27], v[26:27], v[96:97]
	v_div_scale_f32 v51, s[2:3], v50, v50, 1.0
	v_lshlrev_b32_e32 v96, 16, v36
	v_and_b32_e32 v97, 0xffff0000, v36
	v_pk_add_f32 v[4:5], v[4:5], v[6:7]
	v_lshlrev_b32_e32 v6, 16, v39
	v_and_b32_e32 v7, 0xffff0000, v39
	v_lshlrev_b32_e32 v38, 16, v60
	v_and_b32_e32 v39, 0xffff0000, v60
	v_rcp_f32_e32 v60, v51
	v_pk_add_f32 v[26:27], v[26:27], v[96:97]
	v_lshlrev_b32_e32 v96, 16, v28
	v_and_b32_e32 v97, 0xffff0000, v28
	v_pk_add_f32 v[4:5], v[4:5], v[6:7]
	v_lshlrev_b32_e32 v6, 16, v31
	v_and_b32_e32 v7, 0xffff0000, v31
	v_pk_add_f32 v[26:27], v[26:27], v[96:97]
	v_pk_add_f32 v[10:11], v[4:5], v[6:7]
	v_lshlrev_b32_e32 v4, 16, v48
	v_and_b32_e32 v5, 0xffff0000, v48
	v_lshlrev_b32_e32 v6, 16, v49
	v_and_b32_e32 v7, 0xffff0000, v49
	v_lshlrev_b32_e32 v22, 16, v44
	v_and_b32_e32 v23, 0xffff0000, v44
	v_lshlrev_b32_e32 v28, 16, v45
	v_and_b32_e32 v29, 0xffff0000, v45
	v_pk_add_f32 v[4:5], v[26:27], v[4:5]
	v_pk_add_f32 v[6:7], v[8:9], v[6:7]
	v_lshlrev_b32_e32 v44, 16, v61
	v_and_b32_e32 v45, 0xffff0000, v61
	v_fma_f32 v61, -v51, v60, 1.0
	v_pk_add_f32 v[4:5], v[4:5], v[22:23]
	v_pk_add_f32 v[6:7], v[6:7], v[28:29]
	v_fmac_f32_e32 v60, v61, v60
	v_div_scale_f32 v61, vcc, 1.0, v50, 1.0
	v_pk_add_f32 v[4:5], v[4:5], v[38:39]
	v_lshlrev_b32_e32 v22, 16, v16
	v_and_b32_e32 v23, 0xffff0000, v16
	v_pk_add_f32 v[6:7], v[6:7], v[44:45]
	v_lshlrev_b32_e32 v8, 16, v17
	v_and_b32_e32 v9, 0xffff0000, v17
	v_lshlrev_b32_e32 v30, 16, v46
	v_and_b32_e32 v31, 0xffff0000, v46
	v_lshlrev_b32_e32 v36, 16, v47
	v_and_b32_e32 v37, 0xffff0000, v47
	v_lshlrev_b32_e32 v46, 16, v62
	v_and_b32_e32 v47, 0xffff0000, v62
	v_mul_f32_e32 v62, v61, v60
	v_pk_add_f32 v[4:5], v[4:5], v[22:23]
	v_lshlrev_b32_e32 v22, 16, v40
	v_and_b32_e32 v23, 0xffff0000, v40
	v_pk_add_f32 v[6:7], v[6:7], v[8:9]
	v_lshlrev_b32_e32 v8, 16, v41
	v_and_b32_e32 v9, 0xffff0000, v41
	v_lshlrev_b32_e32 v48, 16, v63
	v_and_b32_e32 v49, 0xffff0000, v63
	v_fma_f32 v63, -v51, v62, v61
	v_pk_add_f32 v[4:5], v[4:5], v[22:23]
	v_lshlrev_b32_e32 v22, 16, v32
	v_and_b32_e32 v23, 0xffff0000, v32
	v_pk_add_f32 v[6:7], v[6:7], v[8:9]
	v_lshlrev_b32_e32 v8, 16, v33
	v_and_b32_e32 v9, 0xffff0000, v33
	v_fmac_f32_e32 v62, v63, v60
	v_pk_add_f32 v[4:5], v[4:5], v[22:23]
	v_lshlrev_b32_e32 v22, 16, v56
	v_and_b32_e32 v23, 0xffff0000, v56
	v_pk_add_f32 v[6:7], v[6:7], v[8:9]
	v_lshlrev_b32_e32 v8, 16, v57
	v_and_b32_e32 v9, 0xffff0000, v57
	v_fma_f32 v51, -v51, v62, v61
	v_pk_add_f32 v[4:5], v[4:5], v[22:23]
	v_lshlrev_b32_e32 v22, 16, v52
	v_and_b32_e32 v23, 0xffff0000, v52
	v_pk_add_f32 v[6:7], v[6:7], v[8:9]
	v_lshlrev_b32_e32 v8, 16, v53
	v_and_b32_e32 v9, 0xffff0000, v53
	v_div_fmas_f32 v51, v51, v60, v62
	v_pk_add_f32 v[4:5], v[4:5], v[22:23]
	v_lshlrev_b32_e32 v22, 16, v64
	v_and_b32_e32 v23, 0xffff0000, v64
	v_pk_add_f32 v[6:7], v[6:7], v[8:9]
	v_lshlrev_b32_e32 v8, 16, v65
	v_and_b32_e32 v9, 0xffff0000, v65
	v_div_fixup_f32 v50, v51, v50, 1.0
	v_pk_add_f32 v[4:5], v[4:5], v[22:23]
	v_pk_add_f32 v[6:7], v[6:7], v[8:9]
	v_pk_fma_f32 v[4:5], v[50:51], v[4:5], v[94:95] op_sel_hi:[0,1,1] neg_lo:[0,0,1] neg_hi:[0,0,1]
	v_pk_fma_f32 v[6:7], v[50:51], v[6:7], v[82:83] op_sel_hi:[0,1,1] neg_lo:[0,0,1] neg_hi:[0,0,1]
	v_cvt_pk_bf16_f32 v4, v4, v5
	v_cvt_pk_bf16_f32 v5, v6, v7
	v_pk_add_f32 v[6:7], v[12:13], v[14:15]
	v_lshlrev_b32_e32 v8, 16, v18
	v_pk_add_f32 v[6:7], v[6:7], v[30:31]
	v_and_b32_e32 v9, 0xffff0000, v18
	v_pk_add_f32 v[6:7], v[6:7], v[46:47]
	s_add_i32 s6, s6, s4
	v_pk_add_f32 v[6:7], v[6:7], v[8:9]
	v_lshlrev_b32_e32 v8, 16, v42
	v_and_b32_e32 v9, 0xffff0000, v42
	v_pk_add_f32 v[6:7], v[6:7], v[8:9]
	v_lshlrev_b32_e32 v8, 16, v34
	v_and_b32_e32 v9, 0xffff0000, v34
	v_pk_add_f32 v[6:7], v[6:7], v[8:9]
	v_lshlrev_b32_e32 v8, 16, v58
	v_and_b32_e32 v9, 0xffff0000, v58
	v_pk_add_f32 v[6:7], v[6:7], v[8:9]
	v_lshlrev_b32_e32 v8, 16, v54
	v_and_b32_e32 v9, 0xffff0000, v54
	v_pk_add_f32 v[6:7], v[6:7], v[8:9]
	v_lshlrev_b32_e32 v8, 16, v66
	v_and_b32_e32 v9, 0xffff0000, v66
	v_pk_add_f32 v[6:7], v[6:7], v[8:9]
	v_pk_add_f32 v[8:9], v[10:11], v[20:21]
	v_lshlrev_b32_e32 v10, 16, v19
	v_pk_add_f32 v[8:9], v[8:9], v[36:37]
	v_and_b32_e32 v11, 0xffff0000, v19
	v_pk_add_f32 v[8:9], v[8:9], v[48:49]
	v_pk_fma_f32 v[6:7], v[50:51], v[6:7], v[80:81] op_sel_hi:[0,1,1] neg_lo:[0,0,1] neg_hi:[0,0,1]
	v_pk_add_f32 v[8:9], v[8:9], v[10:11]
	v_lshlrev_b32_e32 v10, 16, v43
	v_and_b32_e32 v11, 0xffff0000, v43
	v_pk_add_f32 v[8:9], v[8:9], v[10:11]
	v_lshlrev_b32_e32 v10, 16, v35
	v_and_b32_e32 v11, 0xffff0000, v35
	v_pk_add_f32 v[8:9], v[8:9], v[10:11]
	v_lshlrev_b32_e32 v10, 16, v59
	v_and_b32_e32 v11, 0xffff0000, v59
	v_pk_add_f32 v[8:9], v[8:9], v[10:11]
	v_lshlrev_b32_e32 v10, 16, v55
	v_and_b32_e32 v11, 0xffff0000, v55
	v_pk_add_f32 v[8:9], v[8:9], v[10:11]
	v_lshlrev_b32_e32 v10, 16, v67
	v_and_b32_e32 v11, 0xffff0000, v67
	v_pk_add_f32 v[8:9], v[8:9], v[10:11]
	v_cvt_pk_bf16_f32 v6, v6, v7
	v_pk_fma_f32 v[8:9], v[50:51], v[8:9], v[24:25] op_sel_hi:[0,1,1] neg_lo:[0,0,1] neg_hi:[0,0,1]
	v_cvt_pk_bf16_f32 v7, v8, v9
	v_add_co_u32_e32 v8, vcc, s5, v78
	s_add_i32 s2, s6, 15
	s_nop 0
	v_addc_co_u32_e32 v9, vcc, 0, v79, vcc
	v_mov_b64_e32 v[150:151], v[8:9]
	v_mov_b64_e32 v[152:153], v[4:5]
	v_mov_b64_e32 v[154:155], v[6:7]
	s_cmp_lt_i32 s2, 0x8000
	v_lshl_add_u64 v[76:77], v[76:77], 0, s[14:15]
	v_lshl_add_u64 v[4:5], s[0:1], 0, v[74:75]
	v_add_co_u32_e32 v6, vcc, s16, v4
	v_lshl_add_u64 v[74:75], v[74:75], 0, s[12:13]
	s_nop 0
	v_addc_co_u32_e32 v7, vcc, 0, v5, vcc
	v_mov_b32_e32 v6, v102
	v_mov_b32_e32 v7, v103
	v_lshlrev_b32_e32 v106, 16, v104
	v_and_b32_e32 v107, 0xffff0000, v104
	v_and_b32_e32 v9, 0xffff0000, v7
	v_and_b32_e32 v11, 0xffff0000, v6
	v_lshlrev_b32_e32 v8, 16, v7
	v_lshlrev_b32_e32 v10, 16, v6
	v_mov_b32_e32 v12, v11
	v_mov_b32_e32 v13, v9
	v_mov_b32_e32 v6, v10
	v_mov_b32_e32 v7, v8
	v_pk_mul_f32 v[12:13], v[12:13], v[12:13]
	s_nop 0
	v_pk_fma_f32 v[6:7], v[6:7], v[6:7], v[12:13]
	s_nop 0
	v_add_f32_e32 v6, v6, v7
	v_pk_mul_f32 v[108:109], v[106:107], v[106:107]
	s_nop 0
	v_add_f32_e32 v108, v108, v109
	s_nop 0
	v_add_f32_dpp v6, v6, v6 quad_perm:[1,0,3,2] row_mask:0xf bank_mask:0xf
	v_add_f32_dpp v108, v108, v108 quad_perm:[1,0,3,2] row_mask:0xf bank_mask:0xf
	s_nop 0
	v_add_f32_dpp v6, v6, v6 quad_perm:[2,3,0,1] row_mask:0xf bank_mask:0xf
	v_add_f32_dpp v108, v108, v108 quad_perm:[2,3,0,1] row_mask:0xf bank_mask:0xf
	s_nop 0
	v_add_f32_dpp v6, v6, v6 row_half_mirror row_mask:0xf bank_mask:0xf
	v_add_f32_dpp v108, v108, v108 row_half_mirror row_mask:0xf bank_mask:0xf
	s_nop 0
	v_add_f32_dpp v6, v6, v6 row_mirror row_mask:0xf bank_mask:0xf
	v_add_f32_dpp v108, v108, v108 row_mirror row_mask:0xf bank_mask:0xf
	s_nop 0
	v_mov_b32_e32 v7, v6
	v_mov_b32_e32 v109, v108
	s_nop 1
	v_permlane16_swap_b32_e32 v6, v7
	v_permlane16_swap_b32_e32 v108, v109
	v_add_f32_e32 v6, v6, v7
	v_add_f32_e32 v108, v108, v109
	v_mov_b32_e32 v7, v6
	v_mov_b32_e32 v109, v108
	s_nop 1
	v_permlane32_swap_b32_e32 v6, v7
	v_permlane32_swap_b32_e32 v108, v109
	v_add_f32_e32 v6, v6, v7
	v_add_f32_e32 v108, v108, v109
	v_fmamk_f32 v6, v6, 0x3b800000, v91
	v_mul_f32_e32 v7, 0x4b800000, v6
	v_cmp_gt_f32_e32 vcc, s17, v6
	s_nop 1
	v_cndmask_b32_e32 v6, v6, v7, vcc
	v_rsq_f32_e32 v6, v6
	s_nop 0
	v_mul_f32_e32 v7, 0x45800000, v6
	v_cndmask_b32_e32 v6, v6, v7, vcc
	v_pk_mul_f32 v[10:11], v[6:7], v[10:11] op_sel_hi:[0,1]
	v_pk_mul_f32 v[6:7], v[6:7], v[8:9] op_sel_hi:[0,1]
	v_pk_mul_f32 v[10:11], v[0:1], v[10:11]
	v_pk_mul_f32 v[6:7], v[2:3], v[6:7]
	v_add_co_u32_e32 v4, vcc, s18, v4
	v_cvt_pk_bf16_f32 v10, v10, v11
	v_cvt_pk_bf16_f32 v11, v6, v7
	v_addc_co_u32_e32 v5, vcc, 0, v5, vcc
	v_mov_b64_e32 v[156:157], v[4:5]
	v_mov_b64_e32 v[158:159], v[10:11]
	v_lshl_add_u64 v[4:5], s[0:1], 0, v[72:73]
	v_lshl_add_u64 v[72:73], v[72:73], 0, s[8:9]
	v_fmamk_f32 v108, v108, 0x3c000000, v91
	v_mul_f32_e32 v109, 0x4b800000, v108
	v_cmp_gt_f32_e32 vcc, s17, v108
	s_nop 1
	v_cndmask_b32_e32 v108, v108, v109, vcc
	v_rsq_f32_e32 v108, v108
	s_nop 0
	v_mul_f32_e32 v109, 0x45800000, v108
	v_cndmask_b32_e32 v108, v108, v109, vcc
	v_pk_mul_f32 v[6:7], v[108:109], v[106:107] op_sel_hi:[0,1]
	v_pk_mul_f32 v[6:7], v[68:69], v[6:7]
	v_add_co_u32_e32 v4, vcc, 0x13a00000, v4
	v_cvt_pk_bf16_f32 v6, v6, v7
	s_nop 0
	v_addc_co_u32_e32 v5, vcc, 0, v5, vcc
	v_mov_b64_e32 v[160:161], v[4:5]
	v_mov_b32_e32 v162, v6
	s_mov_b32 s24, 1
	s_cbranch_scc0 .Lp2_flush

.Lp2_flush:
	global_store_dwordx4 v[150:151], v[152:155], off
	global_store_dwordx2 v[156:157], v[158:159], off
	global_store_dword v[160:161], v162, off
